# prologue weight-conversion item: 8 weight-row + 8 gain loads issued together (one wait) instead of 8 dependent round trips
# baseline (speedup 1.0000x reference)
.LBB0_21:
	s_movk_i32 s4, 0x1ff
	v_cmp_lt_i32_e32 vcc, s4, v196
	s_and_saveexec_b64 s[4:5], vcc
	s_xor_b64 s[6:7], exec, s[4:5]
	s_cbranch_execz .LBB0_39
	v_add_u16_e32 v0, 0xfe00, v196
	v_mul_u32_u24_e32 v1, 0xba2f, v0
	v_lshrrev_b32_e32 v1, 23, v1
	v_mul_lo_u16_e32 v2, 0xb0, v1
	v_sub_u16_e32 v0, v0, v2
	v_lshlrev_b32_e32 v6, 5, v0
	v_lshlrev_b32_e32 v0, 4, v0
	s_load_dwordx4 s[8:11], s[16:17], 0x38
	v_and_b32_e32 v2, 0xe0, v6
	v_and_b32_e32 v0, 0xf80, v0
	s_movk_i32 s4, 0xa80
	v_or_b32_e32 v3, v0, v2
	v_add3_u32 v0, v2, v0, s4
	s_movk_i32 s4, 0x80
	v_cmp_gt_u32_e32 vcc, s4, v2
	v_lshlrev_b16_e32 v7, 6, v1
	v_mov_b32_e32 v57, v53
	v_cndmask_b32_e32 v0, v0, v3, vcc
	v_lshlrev_b32_e32 v52, 2, v0
	s_waitcnt lgkmcnt(0)
	v_lshl_add_u64 v[0:1], s[10:11], 0, v[52:53]
	v_lshl_add_u64 v[4:5], v[0:1], 0, v[56:57]
	v_or_b32_e32 v8, v198, v7
	v_mad_u64_u32 v[0:1], s[10:11], v8, s26, v[4:5]
	global_load_dwordx4 v[12:15], v[0:1], off
	v_or_b32_e32 v9, v199, v7
	v_mad_u64_u32 v[0:1], s[10:11], v9, s26, v[4:5]
	global_load_dwordx4 v[16:19], v[0:1], off
	v_or_b32_e32 v9, v200, v7
	v_mad_u64_u32 v[0:1], s[10:11], v9, s26, v[4:5]
	global_load_dwordx4 v[20:23], v[0:1], off
	v_or_b32_e32 v9, v201, v7
	v_mad_u64_u32 v[0:1], s[10:11], v9, s26, v[4:5]
	global_load_dwordx4 v[24:27], v[0:1], off
	v_or_b32_e32 v9, v202, v7
	v_mad_u64_u32 v[0:1], s[10:11], v9, s26, v[4:5]
	global_load_dwordx4 v[28:31], v[0:1], off
	v_or_b32_e32 v9, v203, v7
	v_mad_u64_u32 v[0:1], s[10:11], v9, s26, v[4:5]
	global_load_dwordx4 v[32:35], v[0:1], off
	v_or_b32_e32 v9, v205, v7
	v_mad_u64_u32 v[0:1], s[10:11], v9, s26, v[4:5]
	global_load_dwordx4 v[36:39], v[0:1], off
	v_or_b32_e32 v9, v206, v7
	v_mad_u64_u32 v[0:1], s[10:11], v9, s26, v[4:5]
	global_load_dwordx4 v[40:43], v[0:1], off
	s_cmp_eq_u64 s[8:9], 0
	s_cbranch_scc1 .Lpro_tr_w
	v_lshlrev_b32_e32 v8, 2, v8
	global_load_dword v44, v8, s[8:9]
	global_load_dword v46, v8, s[8:9] offset:32
	global_load_dword v48, v8, s[8:9] offset:64
	global_load_dword v50, v8, s[8:9] offset:96
	global_load_dword v0, v8, s[8:9] offset:128
	global_load_dword v2, v8, s[8:9] offset:160
	global_load_dword v10, v8, s[8:9] offset:192
	global_load_dword v8, v8, s[8:9] offset:224
	s_waitcnt vmcnt(0)
	v_pk_mul_f32 v[12:13], v[12:13], v[44:45] op_sel_hi:[1,0]
	v_pk_mul_f32 v[14:15], v[14:15], v[44:45] op_sel_hi:[1,0]
	v_pk_mul_f32 v[16:17], v[16:17], v[46:47] op_sel_hi:[1,0]
	v_pk_mul_f32 v[18:19], v[18:19], v[46:47] op_sel_hi:[1,0]
	v_pk_mul_f32 v[20:21], v[20:21], v[48:49] op_sel_hi:[1,0]
	v_pk_mul_f32 v[22:23], v[22:23], v[48:49] op_sel_hi:[1,0]
	v_pk_mul_f32 v[24:25], v[24:25], v[50:51] op_sel_hi:[1,0]
	v_pk_mul_f32 v[26:27], v[26:27], v[50:51] op_sel_hi:[1,0]
	v_pk_mul_f32 v[28:29], v[28:29], v[0:1] op_sel_hi:[1,0]
	v_pk_mul_f32 v[30:31], v[30:31], v[0:1] op_sel_hi:[1,0]
	v_pk_mul_f32 v[32:33], v[32:33], v[2:3] op_sel_hi:[1,0]
	v_pk_mul_f32 v[34:35], v[34:35], v[2:3] op_sel_hi:[1,0]
	v_pk_mul_f32 v[36:37], v[36:37], v[10:11] op_sel_hi:[1,0]
	v_pk_mul_f32 v[38:39], v[38:39], v[10:11] op_sel_hi:[1,0]
	v_pk_mul_f32 v[40:41], v[40:41], v[8:9] op_sel_hi:[1,0]
	v_pk_mul_f32 v[42:43], v[42:43], v[8:9] op_sel_hi:[1,0]
.Lpro_tr_w:
	s_waitcnt vmcnt(0)
	ds_write2_b32 v209, v12, v13 offset1:1
	ds_write2_b32 v209, v14, v15 offset0:2 offset1:3
	v_add_u32_e32 v9, 0x420, v209
	ds_write2_b32 v9, v16, v17 offset1:1
	ds_write2_b32 v9, v18, v19 offset0:2 offset1:3
	v_add_u32_e32 v9, 0x840, v209
	ds_write2_b32 v9, v20, v21 offset1:1
	ds_write2_b32 v9, v22, v23 offset0:2 offset1:3
	v_add_u32_e32 v9, 0xc60, v209
	ds_write2_b32 v9, v24, v25 offset1:1
	ds_write2_b32 v9, v26, v27 offset0:2 offset1:3
	v_add_u32_e32 v9, 0x1080, v209
	ds_write2_b32 v9, v28, v29 offset1:1
	ds_write2_b32 v9, v30, v31 offset0:2 offset1:3
	v_add_u32_e32 v9, 0x14a0, v209
	ds_write2_b32 v9, v32, v33 offset1:1
	ds_write2_b32 v9, v34, v35 offset0:2 offset1:3
	v_add_u32_e32 v9, 0x18c0, v209
	ds_write2_b32 v9, v36, v37 offset1:1
	ds_write2_b32 v9, v38, v39 offset0:2 offset1:3
	v_add_u32_e32 v9, 0x1ce0, v209
	ds_write2_b32 v9, v40, v41 offset1:1
	ds_write2_b32 v9, v42, v43 offset0:2 offset1:3
	s_waitcnt lgkmcnt(0)
	ds_read2_b32 v[4:5], v207 offset1:8
	ds_read2_b32 v[10:11], v207 offset0:33 offset1:41
	ds_read2_b32 v[12:13], v207 offset0:66 offset1:74
	ds_read2_b32 v[14:15], v207 offset0:99 offset1:107
	ds_read2_b32 v[16:17], v207 offset0:132 offset1:140
	s_waitcnt lgkmcnt(4)
	v_bfe_u32 v0, v4, 16, 1
	v_add3_u32 v0, v4, v0, s27
	s_waitcnt lgkmcnt(3)
	v_bfe_u32 v1, v10, 16, 1
	v_lshrrev_b32_e32 v0, 16, v0
	v_add3_u32 v1, v10, v1, s27
	ds_read2_b32 v[18:19], v207 offset0:165 offset1:173
	v_and_or_b32 v0, v1, s28, v0
	s_waitcnt lgkmcnt(3)
	v_bfe_u32 v1, v12, 16, 1
	v_add3_u32 v1, v12, v1, s27
	s_waitcnt lgkmcnt(2)
	v_bfe_u32 v2, v14, 16, 1
	ds_read2_b32 v[20:21], v207 offset0:198 offset1:206
	v_lshrrev_b32_e32 v1, 16, v1
	v_add3_u32 v2, v14, v2, s27
	ds_read2_b32 v[22:23], v207 offset0:231 offset1:239
	v_and_or_b32 v1, v2, s28, v1
	s_waitcnt lgkmcnt(3)
	v_bfe_u32 v2, v16, 16, 1
	v_add3_u32 v2, v16, v2, s27
	s_waitcnt lgkmcnt(2)
	v_bfe_u32 v3, v18, 16, 1
	v_lshrrev_b32_e32 v2, 16, v2
	v_add3_u32 v3, v18, v3, s27
	v_and_or_b32 v2, v3, s28, v2
	s_waitcnt lgkmcnt(1)
	v_bfe_u32 v3, v20, 16, 1
	v_add3_u32 v3, v20, v3, s27
	s_waitcnt lgkmcnt(0)
	v_bfe_u32 v4, v22, 16, 1
	v_lshrrev_b32_e32 v3, 16, v3
	v_add3_u32 v4, v22, v4, s27
	v_lshlrev_b32_e32 v52, 1, v7
	v_and_or_b32 v3, v4, s28, v3
	v_or_b32_e32 v4, v6, v198
	v_lshl_add_u64 v[8:9], v[54:55], 0, v[52:53]
	v_lshlrev_b32_e32 v52, 11, v4
	v_lshl_add_u64 v[24:25], v[8:9], 0, v[52:53]
	global_store_dwordx4 v[24:25], v[0:3], off
	v_bfe_u32 v4, v23, 16, 1
	v_or_b32_e32 v7, v6, v199
	v_bfe_u32 v0, v5, 16, 1
	v_add3_u32 v0, v5, v0, s27
	v_bfe_u32 v1, v11, 16, 1
	v_lshrrev_b32_e32 v0, 16, v0
	v_add3_u32 v1, v11, v1, s27
	v_and_or_b32 v0, v1, s28, v0
	v_bfe_u32 v1, v13, 16, 1
	v_add3_u32 v1, v13, v1, s27
	v_bfe_u32 v2, v15, 16, 1
	v_lshrrev_b32_e32 v1, 16, v1
	v_add3_u32 v2, v15, v2, s27
	v_and_or_b32 v1, v2, s28, v1
	v_bfe_u32 v2, v17, 16, 1
	v_add3_u32 v2, v17, v2, s27
	v_bfe_u32 v3, v19, 16, 1
	v_lshrrev_b32_e32 v2, 16, v2
	v_add3_u32 v3, v19, v3, s27
	v_and_or_b32 v2, v3, s28, v2
	v_bfe_u32 v3, v21, 16, 1
	v_add3_u32 v3, v21, v3, s27
	v_lshrrev_b32_e32 v3, 16, v3
	v_add3_u32 v4, v23, v4, s27
	v_lshlrev_b32_e32 v52, 11, v7
	v_and_or_b32 v3, v4, s28, v3
	ds_read2_b32 v[4:5], v207 offset0:16 offset1:24
	v_lshl_add_u64 v[10:11], v[8:9], 0, v[52:53]
	global_store_dwordx4 v[10:11], v[0:3], off
	ds_read2_b32 v[10:11], v207 offset0:49 offset1:57
	ds_read2_b32 v[12:13], v207 offset0:82 offset1:90
	ds_read2_b32 v[14:15], v207 offset0:115 offset1:123
	s_waitcnt lgkmcnt(3)
	v_bfe_u32 v0, v4, 16, 1
	v_add3_u32 v0, v4, v0, s27
	s_waitcnt lgkmcnt(2)
	v_bfe_u32 v1, v10, 16, 1
	ds_read2_b32 v[16:17], v207 offset0:148 offset1:156
	v_lshrrev_b32_e32 v0, 16, v0
	v_add3_u32 v1, v10, v1, s27
	ds_read2_b32 v[18:19], v207 offset0:181 offset1:189
	v_and_or_b32 v0, v1, s28, v0
	s_waitcnt lgkmcnt(3)
	v_bfe_u32 v1, v12, 16, 1
	v_add3_u32 v1, v12, v1, s27
	s_waitcnt lgkmcnt(2)
	v_bfe_u32 v2, v14, 16, 1
	ds_read2_b32 v[20:21], v207 offset0:214 offset1:222
	v_lshrrev_b32_e32 v1, 16, v1
	v_add3_u32 v2, v14, v2, s27
	ds_read2_b32 v[22:23], v207 offset0:247 offset1:255
	v_and_or_b32 v1, v2, s28, v1
	s_waitcnt lgkmcnt(3)
	v_bfe_u32 v2, v16, 16, 1
	v_add3_u32 v2, v16, v2, s27
	s_waitcnt lgkmcnt(2)
	v_bfe_u32 v3, v18, 16, 1
	v_lshrrev_b32_e32 v2, 16, v2
	v_add3_u32 v3, v18, v3, s27
	v_and_or_b32 v2, v3, s28, v2
	s_waitcnt lgkmcnt(1)
	v_bfe_u32 v3, v20, 16, 1
	v_add3_u32 v3, v20, v3, s27
	s_waitcnt lgkmcnt(0)
	v_bfe_u32 v4, v22, 16, 1
	v_lshrrev_b32_e32 v3, 16, v3
	v_add3_u32 v4, v22, v4, s27
	v_and_or_b32 v3, v4, s28, v3
	v_or_b32_e32 v4, v6, v200
	v_lshlrev_b32_e32 v52, 11, v4
	v_lshl_add_u64 v[24:25], v[8:9], 0, v[52:53]
	global_store_dwordx4 v[24:25], v[0:3], off
	v_bfe_u32 v4, v23, 16, 1
	v_add3_u32 v4, v23, v4, s27
	v_bfe_u32 v0, v5, 16, 1
	v_add3_u32 v0, v5, v0, s27
	v_bfe_u32 v1, v11, 16, 1
	v_lshrrev_b32_e32 v0, 16, v0
	v_add3_u32 v1, v11, v1, s27
	v_and_or_b32 v0, v1, s28, v0
	v_bfe_u32 v1, v13, 16, 1
	v_add3_u32 v1, v13, v1, s27
	v_bfe_u32 v2, v15, 16, 1
	v_lshrrev_b32_e32 v1, 16, v1
	v_add3_u32 v2, v15, v2, s27
	v_and_or_b32 v1, v2, s28, v1
	v_bfe_u32 v2, v17, 16, 1
	v_add3_u32 v2, v17, v2, s27
	v_bfe_u32 v3, v19, 16, 1
	v_lshrrev_b32_e32 v2, 16, v2
	v_add3_u32 v3, v19, v3, s27
	v_and_or_b32 v2, v3, s28, v2
	v_bfe_u32 v3, v21, 16, 1
	v_add3_u32 v3, v21, v3, s27
	v_lshrrev_b32_e32 v3, 16, v3
	v_and_or_b32 v3, v4, s28, v3
	v_or_b32_e32 v4, v6, v201
	v_lshlrev_b32_e32 v52, 11, v4
	v_lshl_add_u64 v[4:5], v[8:9], 0, v[52:53]
	global_store_dwordx4 v[4:5], v[0:3], off
	s_waitcnt lgkmcnt(0)
